# input projection: the 16-column f_a tile runs one K-trip and computes f_a directly with 16x16x32 MFMAs in its epilogue (group 0: 8 rounds + short tail instead of 9)
# baseline (speedup 1.0000x reference)
; template <class Epi, class Sched, bool ALIGN_EPI = false, bool SP2 = false>
; __device__ __forceinline__ void gemm_phase(PG8_LAS unsigned char* lds, const Gemm g, const Sched& S, const Epi& E, const int tid_arg) {
;     ...
;         const bool has_next = S.next(ui + 1, nxt);
;         const char* nA = has_next ? (const char*)g.A + (size_t)nxt.pm * tstep : cA; const char* nB = has_next ? (const char*)g.Bt + (size_t)nxt.pn * tstep : cB;
;         for (int t = 0; t < nt; t += 2) {
;             const bool last = (t == nt - 2);
;     ...
; #pragma unroll
;         for (int a = 0; a < 2; ++a)
; #pragma unroll
;             for (int b = 0; b < 2; ++b)
; #pragma unroll
;                 for (int m = 0; m < 4; ++m)
; #pragma unroll
;                     for (int n = 0; n < 2; ++n) acc[a][b][m][n] = (f32x4){0.f, 0.f, 0.f, 0.f};
;         cur = nxt; cA = nA; cB = nB; ++ui;
.LBB0_362:
	s_ashr_i32 s29, s28, 31
	s_lshl_b64 s[6:7], s[28:29], 19
	s_add_u32 s30, s50, s6
	s_addc_u32 s31, s51, s7
	s_and_b64 s[6:7], s[8:9], exec
	s_cselect_b32 s6, s31, s15
	s_cselect_b32 s7, s30, s14
	s_ashr_i32 s27, s26, 31
	s_lshl_b64 s[34:35], s[26:27], 19
	s_add_u32 s34, s52, s34
	s_addc_u32 s35, s53, s35
	s_and_b64 s[38:39], s[8:9], exec
	s_cselect_b32 s11, s35, s37
	s_cselect_b32 s13, s34, s36
	s_add_u32 s14, s14, 0x40080
	s_addc_u32 s15, s15, 0
	s_add_u32 s27, s36, 0x100
	v_mov_b32_e32 v4, 0
	s_addc_u32 s29, s37, 0
	s_mov_b32 s40, -2
	s_cmp_eq_u32 s10, 32
	s_cselect_b32 s40, 12, -2
	v_mov_b32_e32 v5, v4
	v_mov_b32_e32 v6, v4
	v_mov_b32_e32 v7, v4
	v_mov_b32_e32 v8, v4
	v_mov_b32_e32 v9, v4
	v_mov_b32_e32 v10, v4
	v_mov_b32_e32 v11, v4
	v_mov_b32_e32 v20, v4
	v_mov_b32_e32 v21, v4
	v_mov_b32_e32 v22, v4
	v_mov_b32_e32 v23, v4
	v_mov_b32_e32 v24, v4
	v_mov_b32_e32 v25, v4
	v_mov_b32_e32 v26, v4
	v_mov_b32_e32 v27, v4
	v_mov_b32_e32 v36, v4
	v_mov_b32_e32 v37, v4
	v_mov_b32_e32 v38, v4
	v_mov_b32_e32 v39, v4
	v_mov_b32_e32 v40, v4
	v_mov_b32_e32 v41, v4
	v_mov_b32_e32 v42, v4
	v_mov_b32_e32 v43, v4
	v_mov_b32_e32 v52, v4
	v_mov_b32_e32 v53, v4
	v_mov_b32_e32 v54, v4
	v_mov_b32_e32 v55, v4
	v_mov_b32_e32 v56, v4
	v_mov_b32_e32 v57, v4
	v_mov_b32_e32 v58, v4
	v_mov_b32_e32 v59, v4
	v_mov_b32_e32 v12, v4
	v_mov_b32_e32 v13, v4
	v_mov_b32_e32 v14, v4
	v_mov_b32_e32 v15, v4
	v_mov_b32_e32 v16, v4
	v_mov_b32_e32 v17, v4
	v_mov_b32_e32 v18, v4
	v_mov_b32_e32 v19, v4
	v_mov_b32_e32 v28, v4
	v_mov_b32_e32 v29, v4
	v_mov_b32_e32 v30, v4
	v_mov_b32_e32 v31, v4
	v_mov_b32_e32 v32, v4
	v_mov_b32_e32 v33, v4
	v_mov_b32_e32 v34, v4
	v_mov_b32_e32 v35, v4
	v_mov_b32_e32 v44, v4
	v_mov_b32_e32 v45, v4
	v_mov_b32_e32 v46, v4
	v_mov_b32_e32 v47, v4
	v_mov_b32_e32 v48, v4
	v_mov_b32_e32 v49, v4
	v_mov_b32_e32 v50, v4
	v_mov_b32_e32 v51, v4
	v_mov_b32_e32 v60, v4
	v_mov_b32_e32 v61, v4
	v_mov_b32_e32 v62, v4
	v_mov_b32_e32 v63, v4
	v_mov_b32_e32 v64, v4
	v_mov_b32_e32 v65, v4
	v_mov_b32_e32 v66, v4
	v_mov_b32_e32 v67, v4
	v_mov_b32_e32 v68, v4
	v_mov_b32_e32 v69, v4
	v_mov_b32_e32 v70, v4
	v_mov_b32_e32 v71, v4
	v_mov_b32_e32 v72, v4
	v_mov_b32_e32 v73, v4
	v_mov_b32_e32 v74, v4
	v_mov_b32_e32 v75, v4
	v_mov_b32_e32 v84, v4
	v_mov_b32_e32 v85, v4
	v_mov_b32_e32 v86, v4
	v_mov_b32_e32 v87, v4
	v_mov_b32_e32 v88, v4
	v_mov_b32_e32 v89, v4
	v_mov_b32_e32 v90, v4
	v_mov_b32_e32 v91, v4
	v_mov_b32_e32 v100, v4
	v_mov_b32_e32 v101, v4
	v_mov_b32_e32 v102, v4
	v_mov_b32_e32 v103, v4
	v_mov_b32_e32 v104, v4
	v_mov_b32_e32 v105, v4
	v_mov_b32_e32 v106, v4
	v_mov_b32_e32 v107, v4
	v_mov_b32_e32 v116, v4
	v_mov_b32_e32 v117, v4
	v_mov_b32_e32 v118, v4
	v_mov_b32_e32 v119, v4
	s_waitcnt vmcnt(0)
	v_mov_b32_e32 v120, v4
	v_mov_b32_e32 v121, v4
	v_mov_b32_e32 v122, v4
	v_mov_b32_e32 v123, v4
	v_mov_b32_e32 v76, v4
	v_mov_b32_e32 v77, v4
	v_mov_b32_e32 v78, v4
	v_mov_b32_e32 v79, v4
	v_mov_b32_e32 v80, v4
	v_mov_b32_e32 v81, v4
	v_mov_b32_e32 v82, v4
	v_mov_b32_e32 v83, v4
	v_mov_b32_e32 v92, v4
	v_mov_b32_e32 v93, v4
	v_mov_b32_e32 v94, v4
	v_mov_b32_e32 v95, v4
	v_mov_b32_e32 v96, v4
	v_mov_b32_e32 v97, v4
	v_mov_b32_e32 v98, v4
	v_mov_b32_e32 v99, v4
	v_mov_b32_e32 v108, v4
	v_mov_b32_e32 v109, v4
	v_mov_b32_e32 v110, v4
	v_mov_b32_e32 v111, v4
	v_mov_b32_e32 v112, v4
	v_mov_b32_e32 v113, v4
	v_mov_b32_e32 v114, v4
	v_mov_b32_e32 v115, v4
	v_mov_b32_e32 v124, v4
	v_mov_b32_e32 v125, v4
	v_mov_b32_e32 v126, v4
	v_mov_b32_e32 v127, v4
	v_mov_b32_e32 v128, v4
	v_mov_b32_e32 v129, v4
	v_mov_b32_e32 v130, v4
	v_mov_b32_e32 v131, v4

; __device__ __forceinline__ unsigned cvt_pk_bf16(float lo, float hi) { f32x2_cv v = {lo, hi}; bf16x2_cv b = __builtin_convertvector(v, bf16x2_cv); return __builtin_bit_cast(unsigned, b); }
; __device__ __forceinline__ float rstd_from_ss(const float* ssrow, int fq) {
;     const f32x4 a = ((const f32x4*)ssrow)[fq];
;     float s = (a[0] + a[1]) + (a[2] + a[3]);
;     s += __shfl_xor(s, 16); s += __shfl_xor(s, 32);
;     return rsqrtf(s * (1.0f / 1024.0f) + 1e-6f);
; }
;     __device__ __forceinline__ void operator()(const f32x4 (&acc)[2][2][4][2], const Unit& u, int wr, int wc, int fr, int fq) const {
;     ...
;                 int row = lrow0 + ai * HALF + m * 16; asm volatile("" : "+v"(row));
;                 const float rs = rstd_from_ss(SS + (size_t)row * 16, fq);
;                 if (pn < 32) {
; #pragma unroll
;                     for (int bj = 0; bj < 2; ++bj) {
;                         const f32x4 v0 = acc[ai][bj][m][0] * rs, v1 = acc[ai][bj][m][1] * rs;
;                         u32x4 w; w.x = cvt_pk_bf16(v0[0], v0[1]); w.y = cvt_pk_bf16(v0[2], v0[3]); w.z = cvt_pk_bf16(v1[0], v1[1]); w.w = cvt_pk_bf16(v1[2], v1[3]);
;                         if (pn >= 24) __builtin_nontemporal_store(w, (u32x4*)(dst + (size_t)row * ldc + col0 + bj * HALF)); else *(u32x4*)(dst + (size_t)row * ldc + col0 + bj * HALF) = w;
;                         if (kvo) { float* p = kvo + (size_t)(kvrow0 + row) * 1024 + col0 + bj * HALF; __builtin_nontemporal_store(v0, (f32x4*)p); __builtin_nontemporal_store(v1, (f32x4*)(p + 4)); }
;                     }
;                 } else if (wc == 0 && fq < 2) {
;                     const f32x4 v0 = acc[ai][0][m][0] * rs, v1 = acc[ai][0][m][1] * rs;
;                     float* p = FA + (size_t)row * 16 + 8 * fq; *(f32x4*)p = v0; *(f32x4*)(p + 4) = v1;
.LBB0_374:
	s_cmp_eq_u32 s10, 32
	s_cbranch_scc1 .Lfa_unit
	v_add_u32_e32 v170, s7, v166
	v_mov_b32_e32 v162, v170
	s_cmp_gt_i32 s10, 31
	v_ashrrev_i32_e32 v163, 31, v162
	v_lshlrev_b64 v[156:157], 6, v[162:163]
	v_lshl_add_u64 v[156:157], v[146:147], 0, v[156:157]
	global_load_dwordx4 v[156:159], v[156:157], off
	s_cselect_b64 s[40:41], -1, 0
	s_cmp_lg_u64 s[12:13], 0
	s_cselect_b64 s[10:11], -1, 0
	s_mov_b64 s[42:43], -1
	s_waitcnt vmcnt(0)
	v_mov_b32_e32 v160, v157
	v_mov_b32_e32 v161, v158
	v_mov_b32_e32 v157, v159
	v_pk_add_f32 v[156:157], v[160:161], v[156:157]
	s_nop 0
	v_add_f32_e32 v2, v156, v157
	ds_bpermute_b32 v156, v199, v2
	s_waitcnt lgkmcnt(0)
	v_add_f32_e32 v2, v2, v156
	ds_bpermute_b32 v156, v200, v2
	s_waitcnt lgkmcnt(0)
	v_add_f32_e32 v2, v2, v156
	v_fmamk_f32 v2, v2, 0x3a800000, v140
	v_cmp_gt_f32_e32 vcc, s92, v2
	v_mul_f32_e32 v156, 0x4b800000, v2
	s_nop 0
	v_cndmask_b32_e32 v2, v2, v156, vcc
	v_rsq_f32_e32 v2, v2
	s_nop 0
	v_mul_f32_e32 v156, 0x45800000, v2
	v_cndmask_b32_e32 v160, v2, v156, vcc
	s_and_b64 vcc, exec, s[40:41]
	s_cbranch_vccz .LBB0_378
	s_and_saveexec_b64 s[42:43], s[24:25]
	s_cbranch_execz .LBB0_377
	v_lshlrev_b64 v[156:157], 4, v[162:163]
	v_lshl_add_u64 v[164:165], v[156:157], 2, v[148:149]
	v_pk_mul_f32 v[174:175], v[130:131], v[160:161] op_sel_hi:[1,0]
	v_pk_mul_f32 v[172:173], v[128:129], v[160:161] op_sel_hi:[1,0]
	v_pk_mul_f32 v[158:159], v[126:127], v[160:161] op_sel_hi:[1,0]
	v_pk_mul_f32 v[156:157], v[124:125], v[160:161] op_sel_hi:[1,0]
	global_store_dwordx4 v[164:165], v[172:175], off
	global_store_dwordx4 v[164:165], v[156:159], off offset:16

;     __device__ __forceinline__ void operator()(const f32x4 (&acc)[2][2][4][2], const Unit& u, int wr, int wc, int fr, int fq) const {
;     ...
;                 } else if (wc == 0 && fq < 2) {
;                     const f32x4 v0 = acc[ai][0][m][0] * rs, v1 = acc[ai][0][m][1] * rs;
;                     float* p = FA + (size_t)row * 16 + 8 * fq; *(f32x4*)p = v0; *(f32x4*)(p + 4) = v1;
.Lfa_unit:
	v_lshrrev_b32_e32 v4, 6, v166
	v_lshrrev_b32_e32 v5, 5, v168
	v_and_b32_e32 v6, 15, v166
	v_bfe_u32 v7, v168, 3, 2
	s_nop 0
	v_readfirstlane_b32 s6, v4
	v_readfirstlane_b32 s11, v5
	s_nop 3
	s_lshl_b32 s6, s6, 2
	s_add_i32 s6, s6, s11
	s_lshl_b32 s6, s6, 5
	s_add_i32 s6, s6, s7
	v_add_u32_e32 v114, s6, v6
	v_lshlrev_b32_e32 v115, 4, v7
	v_lshl_add_u32 v108, v114, 11, v115
	v_mov_b32_e32 v109, 0
	v_lshl_add_u64 v[108:109], s[50:51], 0, v[108:109]
	s_mov_b64 s[14:15], 0x8000
	v_lshl_add_u64 v[110:111], v[108:109], 0, s[14:15]
	v_lshl_add_u32 v112, v6, 11, v115
	v_mov_b32_e32 v113, 0
	s_add_u32 s38, s52, 0x1000000
	s_addc_u32 s39, s53, 0
	v_lshl_add_u64 v[112:113], s[38:39], 0, v[112:113]
	v_lshlrev_b32_e32 v116, 6, v114
	v_mov_b32_e32 v117, 0
	v_lshl_add_u64 v[116:117], v[146:147], 0, v[116:117]
	global_load_dwordx4 v[118:121], v[116:117], off
	global_load_dwordx4 v[122:125], v[116:117], off offset:1024
	v_mov_b32_e32 v100, 0
	v_mov_b32_e32 v101, 0
	v_mov_b32_e32 v102, 0
	v_mov_b32_e32 v103, 0
	v_mov_b32_e32 v104, 0
	v_mov_b32_e32 v105, 0
	v_mov_b32_e32 v106, 0
	v_mov_b32_e32 v107, 0
	global_load_dwordx4 v[4:7], v[112:113], off
	global_load_dwordx4 v[8:11], v[112:113], off offset:64
	global_load_dwordx4 v[12:15], v[112:113], off offset:128
	global_load_dwordx4 v[16:19], v[112:113], off offset:192
	global_load_dwordx4 v[20:23], v[112:113], off offset:256
	global_load_dwordx4 v[24:27], v[112:113], off offset:320
	global_load_dwordx4 v[28:31], v[112:113], off offset:384
	global_load_dwordx4 v[32:35], v[112:113], off offset:448
	global_load_dwordx4 v[36:39], v[108:109], off
	global_load_dwordx4 v[40:43], v[108:109], off offset:64
	global_load_dwordx4 v[44:47], v[108:109], off offset:128
	global_load_dwordx4 v[48:51], v[108:109], off offset:192
	global_load_dwordx4 v[52:55], v[108:109], off offset:256
	global_load_dwordx4 v[56:59], v[108:109], off offset:320
	global_load_dwordx4 v[60:63], v[108:109], off offset:384
	global_load_dwordx4 v[64:67], v[108:109], off offset:448
	global_load_dwordx4 v[68:71], v[110:111], off
	global_load_dwordx4 v[72:75], v[110:111], off offset:64
	global_load_dwordx4 v[76:79], v[110:111], off offset:128
	global_load_dwordx4 v[80:83], v[110:111], off offset:192
	global_load_dwordx4 v[84:87], v[110:111], off offset:256
	global_load_dwordx4 v[88:91], v[110:111], off offset:320
	global_load_dwordx4 v[92:95], v[110:111], off offset:384
	global_load_dwordx4 v[96:99], v[110:111], off offset:448
	s_waitcnt vmcnt(0)
	v_mfma_f32_16x16x32_bf16 v[100:103], v[4:7], v[36:39], v[100:103]
	v_mfma_f32_16x16x32_bf16 v[104:107], v[4:7], v[68:71], v[104:107]
	v_mfma_f32_16x16x32_bf16 v[100:103], v[8:11], v[40:43], v[100:103]
	v_mfma_f32_16x16x32_bf16 v[104:107], v[8:11], v[72:75], v[104:107]
	v_mfma_f32_16x16x32_bf16 v[100:103], v[12:15], v[44:47], v[100:103]
	v_mfma_f32_16x16x32_bf16 v[104:107], v[12:15], v[76:79], v[104:107]
	v_mfma_f32_16x16x32_bf16 v[100:103], v[16:19], v[48:51], v[100:103]
	v_mfma_f32_16x16x32_bf16 v[104:107], v[16:19], v[80:83], v[104:107]
	v_mfma_f32_16x16x32_bf16 v[100:103], v[20:23], v[52:55], v[100:103]
	v_mfma_f32_16x16x32_bf16 v[104:107], v[20:23], v[84:87], v[104:107]
	v_mfma_f32_16x16x32_bf16 v[100:103], v[24:27], v[56:59], v[100:103]
	v_mfma_f32_16x16x32_bf16 v[104:107], v[24:27], v[88:91], v[104:107]
	v_mfma_f32_16x16x32_bf16 v[100:103], v[28:31], v[60:63], v[100:103]
	v_mfma_f32_16x16x32_bf16 v[104:107], v[28:31], v[92:95], v[104:107]
	v_mfma_f32_16x16x32_bf16 v[100:103], v[32:35], v[64:67], v[100:103]
	v_mfma_f32_16x16x32_bf16 v[104:107], v[32:35], v[96:99], v[104:107]
	global_load_dwordx4 v[4:7], v[112:113], off offset:512
	global_load_dwordx4 v[8:11], v[112:113], off offset:576
	global_load_dwordx4 v[12:15], v[112:113], off offset:640
	global_load_dwordx4 v[16:19], v[112:113], off offset:704
	global_load_dwordx4 v[20:23], v[112:113], off offset:768
	global_load_dwordx4 v[24:27], v[112:113], off offset:832
	global_load_dwordx4 v[28:31], v[112:113], off offset:896
	global_load_dwordx4 v[32:35], v[112:113], off offset:960
	global_load_dwordx4 v[36:39], v[108:109], off offset:512
	global_load_dwordx4 v[40:43], v[108:109], off offset:576
	global_load_dwordx4 v[44:47], v[108:109], off offset:640
	global_load_dwordx4 v[48:51], v[108:109], off offset:704
	global_load_dwordx4 v[52:55], v[108:109], off offset:768
	global_load_dwordx4 v[56:59], v[108:109], off offset:832
	global_load_dwordx4 v[60:63], v[108:109], off offset:896
	global_load_dwordx4 v[64:67], v[108:109], off offset:960
	global_load_dwordx4 v[68:71], v[110:111], off offset:512
	global_load_dwordx4 v[72:75], v[110:111], off offset:576
	global_load_dwordx4 v[76:79], v[110:111], off offset:640
	global_load_dwordx4 v[80:83], v[110:111], off offset:704
	global_load_dwordx4 v[84:87], v[110:111], off offset:768
	global_load_dwordx4 v[88:91], v[110:111], off offset:832
	global_load_dwordx4 v[92:95], v[110:111], off offset:896
	global_load_dwordx4 v[96:99], v[110:111], off offset:960
	s_waitcnt vmcnt(0)
	v_mfma_f32_16x16x32_bf16 v[100:103], v[4:7], v[36:39], v[100:103]
	v_mfma_f32_16x16x32_bf16 v[104:107], v[4:7], v[68:71], v[104:107]
	v_mfma_f32_16x16x32_bf16 v[100:103], v[8:11], v[40:43], v[100:103]
	v_mfma_f32_16x16x32_bf16 v[104:107], v[8:11], v[72:75], v[104:107]
	v_mfma_f32_16x16x32_bf16 v[100:103], v[12:15], v[44:47], v[100:103]
	v_mfma_f32_16x16x32_bf16 v[104:107], v[12:15], v[76:79], v[104:107]
	v_mfma_f32_16x16x32_bf16 v[100:103], v[16:19], v[48:51], v[100:103]
	v_mfma_f32_16x16x32_bf16 v[104:107], v[16:19], v[80:83], v[104:107]
	v_mfma_f32_16x16x32_bf16 v[100:103], v[20:23], v[52:55], v[100:103]
	v_mfma_f32_16x16x32_bf16 v[104:107], v[20:23], v[84:87], v[104:107]
	v_mfma_f32_16x16x32_bf16 v[100:103], v[24:27], v[56:59], v[100:103]
	v_mfma_f32_16x16x32_bf16 v[104:107], v[24:27], v[88:91], v[104:107]
	v_mfma_f32_16x16x32_bf16 v[100:103], v[28:31], v[60:63], v[100:103]
	v_mfma_f32_16x16x32_bf16 v[104:107], v[28:31], v[92:95], v[104:107]
	v_mfma_f32_16x16x32_bf16 v[100:103], v[32:35], v[64:67], v[100:103]
	v_mfma_f32_16x16x32_bf16 v[104:107], v[32:35], v[96:99], v[104:107]
	global_load_dwordx4 v[4:7], v[112:113], off offset:1024
	global_load_dwordx4 v[8:11], v[112:113], off offset:1088
	global_load_dwordx4 v[12:15], v[112:113], off offset:1152
	global_load_dwordx4 v[16:19], v[112:113], off offset:1216
	global_load_dwordx4 v[20:23], v[112:113], off offset:1280
	global_load_dwordx4 v[24:27], v[112:113], off offset:1344
	global_load_dwordx4 v[28:31], v[112:113], off offset:1408
	global_load_dwordx4 v[32:35], v[112:113], off offset:1472
	global_load_dwordx4 v[36:39], v[108:109], off offset:1024
	global_load_dwordx4 v[40:43], v[108:109], off offset:1088
	global_load_dwordx4 v[44:47], v[108:109], off offset:1152
	global_load_dwordx4 v[48:51], v[108:109], off offset:1216
	global_load_dwordx4 v[52:55], v[108:109], off offset:1280
	global_load_dwordx4 v[56:59], v[108:109], off offset:1344
	global_load_dwordx4 v[60:63], v[108:109], off offset:1408
	global_load_dwordx4 v[64:67], v[108:109], off offset:1472
	global_load_dwordx4 v[68:71], v[110:111], off offset:1024
	global_load_dwordx4 v[72:75], v[110:111], off offset:1088
	global_load_dwordx4 v[76:79], v[110:111], off offset:1152
	global_load_dwordx4 v[80:83], v[110:111], off offset:1216
	global_load_dwordx4 v[84:87], v[110:111], off offset:1280
	global_load_dwordx4 v[88:91], v[110:111], off offset:1344
	global_load_dwordx4 v[92:95], v[110:111], off offset:1408
	global_load_dwordx4 v[96:99], v[110:111], off offset:1472
	s_waitcnt vmcnt(0)
	v_mfma_f32_16x16x32_bf16 v[100:103], v[4:7], v[36:39], v[100:103]
	v_mfma_f32_16x16x32_bf16 v[104:107], v[4:7], v[68:71], v[104:107]
	v_mfma_f32_16x16x32_bf16 v[100:103], v[8:11], v[40:43], v[100:103]
	v_mfma_f32_16x16x32_bf16 v[104:107], v[8:11], v[72:75], v[104:107]
	v_mfma_f32_16x16x32_bf16 v[100:103], v[12:15], v[44:47], v[100:103]
	v_mfma_f32_16x16x32_bf16 v[104:107], v[12:15], v[76:79], v[104:107]
	v_mfma_f32_16x16x32_bf16 v[100:103], v[16:19], v[48:51], v[100:103]
	v_mfma_f32_16x16x32_bf16 v[104:107], v[16:19], v[80:83], v[104:107]
	v_mfma_f32_16x16x32_bf16 v[100:103], v[20:23], v[52:55], v[100:103]
	v_mfma_f32_16x16x32_bf16 v[104:107], v[20:23], v[84:87], v[104:107]
	v_mfma_f32_16x16x32_bf16 v[100:103], v[24:27], v[56:59], v[100:103]
	v_mfma_f32_16x16x32_bf16 v[104:107], v[24:27], v[88:91], v[104:107]
	v_mfma_f32_16x16x32_bf16 v[100:103], v[28:31], v[60:63], v[100:103]
	v_mfma_f32_16x16x32_bf16 v[104:107], v[28:31], v[92:95], v[104:107]
	v_mfma_f32_16x16x32_bf16 v[100:103], v[32:35], v[64:67], v[100:103]
	v_mfma_f32_16x16x32_bf16 v[104:107], v[32:35], v[96:99], v[104:107]
	global_load_dwordx4 v[4:7], v[112:113], off offset:1536
	global_load_dwordx4 v[8:11], v[112:113], off offset:1600
	global_load_dwordx4 v[12:15], v[112:113], off offset:1664
	global_load_dwordx4 v[16:19], v[112:113], off offset:1728
	global_load_dwordx4 v[20:23], v[112:113], off offset:1792
	global_load_dwordx4 v[24:27], v[112:113], off offset:1856
	global_load_dwordx4 v[28:31], v[112:113], off offset:1920
	global_load_dwordx4 v[32:35], v[112:113], off offset:1984
	global_load_dwordx4 v[36:39], v[108:109], off offset:1536
	global_load_dwordx4 v[40:43], v[108:109], off offset:1600
	global_load_dwordx4 v[44:47], v[108:109], off offset:1664
	global_load_dwordx4 v[48:51], v[108:109], off offset:1728
	global_load_dwordx4 v[52:55], v[108:109], off offset:1792
	global_load_dwordx4 v[56:59], v[108:109], off offset:1856
	global_load_dwordx4 v[60:63], v[108:109], off offset:1920
	global_load_dwordx4 v[64:67], v[108:109], off offset:1984
	global_load_dwordx4 v[68:71], v[110:111], off offset:1536
	global_load_dwordx4 v[72:75], v[110:111], off offset:1600
	global_load_dwordx4 v[76:79], v[110:111], off offset:1664
	global_load_dwordx4 v[80:83], v[110:111], off offset:1728
	global_load_dwordx4 v[84:87], v[110:111], off offset:1792
	global_load_dwordx4 v[88:91], v[110:111], off offset:1856
	global_load_dwordx4 v[92:95], v[110:111], off offset:1920
	global_load_dwordx4 v[96:99], v[110:111], off offset:1984
	s_waitcnt vmcnt(0)
; __device__ __forceinline__ float rstd_from_ss(const float* ssrow, int fq) {
;     const f32x4 a = ((const f32x4*)ssrow)[fq];
;     float s = (a[0] + a[1]) + (a[2] + a[3]);
;     s += __shfl_xor(s, 16); s += __shfl_xor(s, 32);
;     return rsqrtf(s * (1.0f / 1024.0f) + 1e-6f);
;     __device__ __forceinline__ void operator()(const f32x4 (&acc)[2][2][4][2], const Unit& u, int wr, int wc, int fr, int fq) const {
;     ...
;                 } else if (wc == 0 && fq < 2) {
;                     const f32x4 v0 = acc[ai][0][m][0] * rs, v1 = acc[ai][0][m][1] * rs;
;                     float* p = FA + (size_t)row * 16 + 8 * fq; *(f32x4*)p = v0; *(f32x4*)(p + 4) = v1;
	v_mfma_f32_16x16x32_bf16 v[100:103], v[4:7], v[36:39], v[100:103]
	v_mfma_f32_16x16x32_bf16 v[104:107], v[4:7], v[68:71], v[104:107]
	v_mfma_f32_16x16x32_bf16 v[100:103], v[8:11], v[40:43], v[100:103]
	v_mfma_f32_16x16x32_bf16 v[104:107], v[8:11], v[72:75], v[104:107]
	v_mfma_f32_16x16x32_bf16 v[100:103], v[12:15], v[44:47], v[100:103]
	v_mfma_f32_16x16x32_bf16 v[104:107], v[12:15], v[76:79], v[104:107]
	v_mfma_f32_16x16x32_bf16 v[100:103], v[16:19], v[48:51], v[100:103]
	v_mfma_f32_16x16x32_bf16 v[104:107], v[16:19], v[80:83], v[104:107]
	v_mfma_f32_16x16x32_bf16 v[100:103], v[20:23], v[52:55], v[100:103]
	v_mfma_f32_16x16x32_bf16 v[104:107], v[20:23], v[84:87], v[104:107]
	v_mfma_f32_16x16x32_bf16 v[100:103], v[24:27], v[56:59], v[100:103]
	v_mfma_f32_16x16x32_bf16 v[104:107], v[24:27], v[88:91], v[104:107]
	v_mfma_f32_16x16x32_bf16 v[100:103], v[28:31], v[60:63], v[100:103]
	v_mfma_f32_16x16x32_bf16 v[104:107], v[28:31], v[92:95], v[104:107]
	v_mfma_f32_16x16x32_bf16 v[100:103], v[32:35], v[64:67], v[100:103]
	v_mfma_f32_16x16x32_bf16 v[104:107], v[32:35], v[96:99], v[104:107]
	v_add_f32_e32 v118, v119, v118
	v_add_f32_e32 v119, v120, v121
	v_add_f32_e32 v118, v118, v119
	ds_bpermute_b32 v119, v199, v118
	s_waitcnt lgkmcnt(0)
	v_add_f32_e32 v118, v118, v119
	ds_bpermute_b32 v119, v200, v118
	s_waitcnt lgkmcnt(0)
	v_add_f32_e32 v118, v118, v119
	v_fmamk_f32 v118, v118, 0x3a800000, v140
	v_cmp_gt_f32_e32 vcc, s92, v118
	v_mul_f32_e32 v119, 0x4b800000, v118
	s_nop 0
	v_cndmask_b32_e32 v118, v118, v119, vcc
	v_rsq_f32_e32 v118, v118
	s_nop 0
	v_mul_f32_e32 v119, 0x45800000, v118
	v_cndmask_b32_e32 v118, v118, v119, vcc
	v_add_f32_e32 v122, v123, v122
	v_add_f32_e32 v123, v124, v125
	v_add_f32_e32 v122, v122, v123
	ds_bpermute_b32 v123, v199, v122
	s_waitcnt lgkmcnt(0)
	v_add_f32_e32 v122, v122, v123
	ds_bpermute_b32 v123, v200, v122
	s_waitcnt lgkmcnt(0)
	v_add_f32_e32 v122, v122, v123
	v_fmamk_f32 v122, v122, 0x3a800000, v140
	v_cmp_gt_f32_e32 vcc, s92, v122
	v_mul_f32_e32 v123, 0x4b800000, v122
	s_nop 0
	v_cndmask_b32_e32 v122, v122, v123, vcc
	v_rsq_f32_e32 v122, v122
	s_nop 0
	v_mul_f32_e32 v123, 0x45800000, v122
	v_cndmask_b32_e32 v122, v122, v123, vcc
	v_mul_f32_e32 v100, v100, v118
	v_mul_f32_e32 v101, v101, v118
	v_mul_f32_e32 v102, v102, v118
	v_mul_f32_e32 v103, v103, v118
	v_mul_f32_e32 v104, v104, v122
	v_mul_f32_e32 v105, v105, v122
	v_mul_f32_e32 v106, v106, v122
	v_mul_f32_e32 v107, v107, v122
	v_sub_co_u32_e32 v126, vcc, v148, v115
	s_nop 1
	v_subbrev_co_u32_e32 v127, vcc, 0, v149, vcc
	v_lshlrev_b32_e32 v128, 6, v114
	v_mov_b32_e32 v129, 0
	v_lshl_add_u64 v[126:127], v[126:127], 0, v[128:129]
	global_store_dwordx4 v[126:127], v[100:103], off
	global_store_dwordx4 v[126:127], v[104:107], off offset:1024
	s_branch .LBB0_446
	s_nop 0
	s_nop 0
	s_nop 0
	s_nop 0
	s_nop 0
	s_nop 0
